# launch-constant grid size: 13 scalar kernarg loads + waits in tile/job/item loops replaced by an immediate (on top of v34)
# speedup vs baseline: 1.0087x; 1.0087x over previous
; __device__ __forceinline__ int fresh_bid() { int t; asm volatile("s_mov_b32 %0, %1" : "=s"(t) : "s"(blockIdx.x)); return t; }
; #define ACC_ZERO(acc) _Pragma("unroll") for (int _a = 0; _a < 2; ++_a) _Pragma("unroll") for (int _b = 0; _b < 2; ++_b) _Pragma("unroll") for (int _m = 0; _m < 4; ++_m) \
;     _Pragma("unroll") for (int _n = 0; _n < 2; ++_n) acc[_a][_b][_m][_n] = (f32x4){0.f, 0.f, 0.f, 0.f}
; __device__ __forceinline__ void phase_resid_gemm(const Ctx& a, const bf16_t* A, int K, const bf16_t* W, const float* xsrc, float alpha, LAS unsigned char* lds) {
;     ...
;     for (int w = fresh_bid(); w < ntile; w += gridDim.x) {
;         int pm, pn; tile_of(w, nM, pm, pn);
;         Acc acc; ACC_ZERO(acc);
;         gemm_kloop(acc, A, K, W, K, pm * 256, pn * 256, K / 64, lds);
;         __syncthreads();
;         epi_resid(acc, pm, pn, xsrc, a.out, xb, ssq, alpha, lds);
;         __syncthreads();
.LBB0_92:
	s_or_b64 exec, exec, s[36:37]
	s_barrier
	s_movk_i32 s8, 0x100
	s_waitcnt lgkmcnt(0)
	s_add_i32 s26, s8, s26

; #define LAS __attribute__((address_space(3)))
; __device__ __forceinline__ int fresh_tid() { int t; asm volatile("v_mov_b32 %0, %1" : "=v"(t) : "v"(threadIdx.x)); return t; }
; __device__ __forceinline__ int fresh_bid() { int t; asm volatile("s_mov_b32 %0, %1" : "=s"(t) : "s"(blockIdx.x)); return t; }
; #define ACC_ZERO(acc) _Pragma("unroll") for (int _a = 0; _a < 2; ++_a) _Pragma("unroll") for (int _b = 0; _b < 2; ++_b) _Pragma("unroll") for (int _m = 0; _m < 4; ++_m) \
;     _Pragma("unroll") for (int _n = 0; _n < 2; ++_n) acc[_a][_b][_m][_n] = (f32x4){0.f, 0.f, 0.f, 0.f}
; __device__ __forceinline__ void gemm_stage_first(const bf16_t* __restrict__ A, int lda, const bf16_t* __restrict__ Bt, int ldb, int brow, int bcol, LAS unsigned char* lds) {
;     const int tid = fresh_tid();
;     const int wvu = __builtin_amdgcn_readfirstlane(tid >> 6);
;     unsigned offA, offB;
;     { int _r, _c; stage_rc(tid * 16, _r, _c); offA = (unsigned)(_r * lda + _c) * 2u; offB = (unsigned)(_r * ldb + _c) * 2u; }
;     STAGE(SBo(0, 0), Bt, ldb, bcol, 0, offB); STAGE(SAo(0, 0), A, lda, brow, 0, offA);
;     STAGE(SBo(0, 1), Bt, ldb, bcol + HALF, 0, offB); STAGE(SAo(0, 1), A, lda, brow + HALF, 0, offA);
; }
; __device__ __forceinline__ void phase_ffn1(const Ctx& a, const bf16_t* W, LAS unsigned char* lds) {
;     ...
;     for (int w = fresh_bid(); w < ntile; w += gridDim.x) {
;         int pm, pn; tile_of(w, nM, pm, pn);
;         Acc acc; ACC_ZERO(acc);
;         gemm_kloop<true>(acc, xb, DM, W, DM, pm * 256, pn * 256, DM / 64, lds);
;         { const int wn = w + (int)gridDim.x; if (wn < ntile) { int pm2, pn2; tile_of(wn, nM, pm2, pn2); gemm_stage_first(xb, DM, W, DM, pm2 * 256, pn2 * 256, lds); } }
.LBB0_133:
	s_or_b64 exec, exec, s[12:13]
	s_movk_i32 s1, 0x100
	s_waitcnt lgkmcnt(0)
	s_add_i32 s26, s1, s26
	s_cmpk_gt_i32 s26, 0x57f
	s_cselect_b64 s[12:13], -1, 0
	s_and_b64 vcc, exec, s[12:13]
	s_cbranch_vccnz .LBB0_126
	s_ashr_i32 s1, s26, 31
	s_lshr_b32 s1, s1, 26
	s_add_i32 s1, s26, s1
	v_mov_b32 v1, v179
	s_and_b32 s30, s1, 0xffffc0
	v_ashrrev_i32_e32 v131, 31, v1
	s_lshl_b32 s1, s1, 2
	v_lshrrev_b32_e32 v131, 26, v131
	s_and_b32 s42, s1, 0xffffff00
	v_readfirstlane_b32 s1, v1
	v_lshlrev_b32_e32 v130, 4, v1
	v_add_u32_e32 v131, v1, v131
	v_bfe_i32 v1, v1, 27, 1
	v_lshrrev_b32_e32 v1, 22, v1
	v_add_u32_e32 v1, v130, v1
	v_and_b32_e32 v1, 0xfffffc00, v1
	v_sub_u32_e32 v1, v130, v1
	v_lshrrev_b32_e32 v130, 4, v1
	v_bitop3_b32 v130, v130, v1, 32 bitop3:0x6c
	v_ashrrev_i32_e32 v1, 31, v1
	v_lshrrev_b32_e32 v1, 26, v1
	v_add_u32_e32 v1, v130, v1
	s_sub_i32 s30, s26, s30
	s_ashr_i32 s1, s1, 6
	v_ashrrev_i32_e32 v1, 6, v1
	s_lshl_b32 s40, s30, 8
	v_ashrrev_i32_e32 v131, 6, v131
	v_mul_i32_i24_e32 v133, 64, v1
	s_mov_b32 s44, s27
	s_mov_b32 s30, s1
	v_lshlrev_b32_e32 v132, 3, v131
	v_lshlrev_b32_e32 v131, 5, v131
	v_sub_u32_e32 v130, v130, v133
	s_ashr_i32 s45, s44, 31
	v_and_b32_e32 v132, 0x1ffff0, v132
	v_and_b32_e32 v131, 32, v131
	v_ashrrev_i16_sdwa v130, v194, sext(v130) dst_sel:DWORD dst_unused:UNUSED_PAD src0_sel:DWORD src1_sel:BYTE_0
	s_lshl_b64 s[44:45], s[44:45], 7
	v_add_u32_sdwa v130, v131, sext(v130) dst_sel:DWORD dst_unused:UNUSED_PAD src0_sel:DWORD src1_sel:WORD_0
	v_add_lshl_u32 v1, v1, v132, 11
	s_add_u32 s44, s76, s44
	v_lshl_add_u32 v144, v130, 1, v1
	s_addc_u32 s45, s77, s45
	s_ashr_i32 s43, s42, 31
	v_lshl_add_u64 v[130:131], s[44:45], 0, v[144:145]
	s_lshl_b64 s[44:45], s[42:43], 11
	s_lshl_b32 s30, s30, 10
	v_lshl_add_u64 v[132:133], v[130:131], 0, s[44:45]
	s_or_b32 s44, s42, 64
	s_add_i32 s30, s30, 0
	s_ashr_i32 s45, s44, 31
	s_add_i32 m0, s30, 0x10000
	s_lshl_b64 s[44:45], s[44:45], 11
	global_load_lds_dwordx4 v[132:133], off
	v_lshl_add_u64 v[130:131], v[130:131], 0, s[44:45]
	s_add_i32 m0, s30, 0x12000
	s_mov_b32 s44, s27
	s_mov_b32 s30, s1
	global_load_lds_dwordx4 v[130:131], off
	s_ashr_i32 s45, s44, 31
	s_lshl_b64 s[44:45], s[44:45], 7
	s_add_u32 s44, s34, s44
	s_addc_u32 s45, s35, s45
	s_ashr_i32 s41, s40, 31
	v_lshl_add_u64 v[130:131], s[44:45], 0, v[144:145]
	s_lshl_b64 s[44:45], s[40:41], 11
	s_lshl_b32 s30, s30, 10
	v_lshl_add_u64 v[132:133], v[130:131], 0, s[44:45]
	s_or_b32 s44, s40, 64
	s_add_i32 s30, s30, 0
	s_ashr_i32 s45, s44, 31
	s_mov_b32 m0, s30
	s_lshl_b64 s[44:45], s[44:45], 11
	global_load_lds_dwordx4 v[132:133], off
	v_lshl_add_u64 v[130:131], v[130:131], 0, s[44:45]
	s_add_i32 m0, s30, 0x2000
	s_mov_b32 s44, s27
	s_mov_b32 s30, s1
	global_load_lds_dwordx4 v[130:131], off
	s_ashr_i32 s45, s44, 31
	s_or_b32 s46, s42, 0x80
	s_lshl_b64 s[44:45], s[44:45], 7
	s_add_u32 s44, s76, s44
	s_addc_u32 s45, s77, s45
	s_lshl_b32 s30, s30, 10
	s_ashr_i32 s47, s46, 31
	s_or_b32 s42, s42, 0xc0
	v_lshl_add_u64 v[130:131], s[44:45], 0, v[144:145]
	s_add_i32 s30, s30, 0
	s_lshl_b64 s[44:45], s[46:47], 11
	s_ashr_i32 s43, s42, 31
	s_add_i32 m0, s30, 0x14000
	v_lshl_add_u64 v[132:133], v[130:131], 0, s[44:45]
	s_lshl_b64 s[42:43], s[42:43], 11
	global_load_lds_dwordx4 v[132:133], off
	v_lshl_add_u64 v[130:131], v[130:131], 0, s[42:43]
	s_add_i32 m0, s30, 0x16000
	s_mov_b32 s42, s27
	global_load_lds_dwordx4 v[130:131], off
	s_ashr_i32 s43, s42, 31
	s_or_b32 s44, s40, 0x80
	s_lshl_b64 s[42:43], s[42:43], 7
	s_add_u32 s42, s34, s42
	s_addc_u32 s43, s35, s43
	s_lshl_b32 s1, s1, 10
	s_ashr_i32 s45, s44, 31
	s_or_b32 s40, s40, 0xc0
	v_lshl_add_u64 v[130:131], s[42:43], 0, v[144:145]
	s_add_i32 s1, s1, 0
	s_lshl_b64 s[42:43], s[44:45], 11
	s_ashr_i32 s41, s40, 31
	s_add_i32 m0, s1, 0x4000
	v_lshl_add_u64 v[132:133], v[130:131], 0, s[42:43]
	s_lshl_b64 s[40:41], s[40:41], 11
	global_load_lds_dwordx4 v[132:133], off
	v_lshl_add_u64 v[130:131], v[130:131], 0, s[40:41]
	s_add_i32 m0, s1, 0x6000
	s_nop 0
	global_load_lds_dwordx4 v[130:131], off
	s_branch .LBB0_126

; #define LAS __attribute__((address_space(3)))
; __device__ __forceinline__ float lo_bf(unsigned u) { return __uint_as_float(u << 16); }
; __device__ __forceinline__ float hi_bf(unsigned u) { return __uint_as_float(u & 0xffff0000u); }
; __device__ __forceinline__ int fresh_tid() { int t; asm volatile("v_mov_b32 %0, %1" : "=v"(t) : "v"(threadIdx.x)); return t; }
; __device__ __forceinline__ int fresh_bid() { int t; asm volatile("s_mov_b32 %0, %1" : "=s"(t) : "s"(blockIdx.x)); return t; }
; __device__ __forceinline__ void phase_post2(const Ctx& a, int l, LAS unsigned char* lds) {
;     bf16_t* mr = (bf16_t*)(a.ws + B_MLA); const bf16_t* pa = (const bf16_t*)(a.ws + B_PROJ); bf16_t* kro = (bf16_t*)(a.ws + B_KROPE);
;     const float2* t32 = (const float2*)(a.ws + WS_TAB32);
;     const float* gq = a.in(I_QN) + l * 96; const float* gk = a.in(I_KN) + l * 96;
;     const int lane = fresh_tid() & 63, wv = fresh_tid() >> 6, h = lane >> 3, j = lane & 7;
;     const float QS = 0.10206207261596575f * LOG2E;
;     for (int tk = fresh_bid() * 8 + wv; tk < SEQ; tk += gridDim.x * 8) {
;         const float2 cs0 = t32[tk * 16 + 2 * j], cs1 = t32[tk * 16 + 2 * j + 1];
;         const u32x4 nvk = *(const u32x4*)(mr + (size_t)tk * MR + 768 + h * 128 + j * 8);
;         const unsigned avk = *(const unsigned*)(pa + (size_t)tk * PA + C_KR + 2 * j), bvk = *(const unsigned*)(pa + (size_t)tk * PA + C_KR + 16 + 2 * j);
;         {
;             bf16_t* q = mr + (size_t)tk * MR + h * 96;
;             u32x4 nv = *(const u32x4*)(q + j * 8);
;             unsigned av = *(const unsigned*)(q + 64 + 2 * j), bv = *(const unsigned*)(q + 80 + 2 * j);
;             float x[8]; x[0] = lo_bf(nv[0]); x[1] = hi_bf(nv[0]); x[2] = lo_bf(nv[1]); x[3] = hi_bf(nv[1]); x[4] = lo_bf(nv[2]); x[5] = hi_bf(nv[2]); x[6] = lo_bf(nv[3]); x[7] = hi_bf(nv[3]);
;             float a0 = lo_bf(av), a1 = hi_bf(av), b0 = lo_bf(bv), b1 = hi_bf(bv);
;             float ss = a0 * a0 + a1 * a1 + b0 * b0 + b1 * b1;
; #pragma unroll
;             for (int e = 0; e < 8; ++e) ss += x[e] * x[e];
;             ss += __shfl_xor(ss, 1); ss += __shfl_xor(ss, 2); ss += __shfl_xor(ss, 4);
;             float r = rsqrtf(ss * (1.f / 96.f) + EPS) * QS;
.LBB0_303:
	v_readlane_b32 s0, v254, 36
	v_readlane_b32 s1, v254, 37
	s_waitcnt lgkmcnt(0)
	s_nop 3
	global_load_dwordx4 v[2:5], v145, s[0:1]
	v_mov_b32 v1, v179
	s_waitcnt vmcnt(0)
	v_mov_b32 v6, v179
	s_mov_b32 s12, s2
	s_movk_i32 s0, 0x2000
	v_ashrrev_i32_e32 v6, 6, v6
	v_lshl_add_u32 v14, s12, 3, v6
	v_cmp_gt_i32_e32 vcc, s0, v14
	s_and_saveexec_b64 s[0:1], vcc
	v_readlane_b32 s6, v254, 1
	v_readlane_b32 s40, v254, 32
	s_movk_i32 s38, 0xe00
	s_movk_i32 s39, 0x1fff
	v_readlane_b32 s7, v254, 2
	v_readlane_b32 s41, v254, 33
	s_cbranch_execz .LBB0_306
	v_and_b32_e32 v11, 64, v195
	v_readlane_b32 s8, v255, 17
	v_and_b32_e32 v7, 7, v1
	v_bfe_u32 v9, v1, 3, 3
	v_xor_b32_e32 v1, 1, v195
	v_add_u32_e32 v11, 64, v11
	v_readlane_b32 s9, v255, 18
	v_cmp_lt_i32_e32 vcc, v1, v11
	v_xor_b32_e32 v15, 2, v195
	v_lshl_add_u64 v[4:5], v[4:5], 0, s[8:9]
	v_lshl_add_u64 v[2:3], v[2:3], 0, s[8:9]
	v_cndmask_b32_e32 v1, v195, v1, vcc
	v_cmp_lt_i32_e32 vcc, v15, v11
	s_movk_i32 s8, 0x100
	v_readlane_b32 s36, v254, 34
	v_cndmask_b32_e32 v15, v195, v15, vcc
	v_lshlrev_b32_e32 v144, 6, v9
	v_readlane_b32 s37, v254, 35
	v_lshlrev_b32_e32 v12, 3, v7
	v_mov_b32_e32 v13, v145
	v_lshlrev_b32_e32 v70, 2, v15
	v_xor_b32_e32 v15, 4, v195
	v_lshl_add_u64 v[24:25], s[36:37], 0, v[144:145]
	v_lshlrev_b32_e32 v144, 5, v7
	v_cmp_lt_i32_e32 vcc, v15, v11
	v_lshl_add_u64 v[16:17], v[2:3], 0, v[12:13]
	v_lshl_add_u64 v[22:23], v[2:3], 0, v[144:145]
	v_lshlrev_b32_e32 v2, 4, v6
	v_lshlrev_b32_e32 v8, 1, v7
	v_lshlrev_b32_e32 v10, 7, v9
	v_mul_u32_u24_e32 v32, 0x60, v9
	v_cndmask_b32_e32 v11, v195, v15, vcc
	v_lshl_add_u64 v[20:21], v[4:5], 0, v[144:145]
	v_lshlrev_b32_e32 v144, 2, v7
	v_lshl_add_u32 v2, s12, 7, v2
	v_lshlrev_b32_e32 v1, 2, v1
	v_lshlrev_b32_e32 v71, 2, v11
	v_lshl_add_u64 v[18:19], v[4:5], 0, v[12:13]
	s_waitcnt lgkmcnt(0)
	s_lshl_b32 s9, s8, 3
	v_lshl_add_u64 v[24:25], v[24:25], 0, v[144:145]
	v_or_b32_e32 v26, v2, v8
	s_lshl_b32 s26, s8, 7
	s_mov_b64 s[12:13], 0
	v_lshlrev_b32_e32 v144, 1, v10
	v_lshlrev_b32_e32 v28, 1, v12
	v_lshlrev_b32_e32 v30, 1, v8
	v_lshlrev_b32_e32 v32, 1, v32

; __device__ __forceinline__ int fresh_bid() { int t; asm volatile("s_mov_b32 %0, %1" : "=s"(t) : "s"(blockIdx.x)); return t; }
; __device__ __forceinline__ void moba_gate_item(const Ctx& a, int tb, LAS unsigned char* lds) {
;     ...
;     unsigned m = 1u << qb;
;     if (i1 >= 0) m |= 1u << i1;
;     if (i2 >= 0) m |= 1u << i2;
;     if (i3 >= 0) m |= 1u << i3;
;     mask[(size_t)h * SEQ + tk] = m;
;     __syncthreads();
; __global__ void __launch_bounds__(NT, 2) mk_fwd(Args a_in) {
;     ...
;                 for (int it = fresh_bid(); it < 128; it += gridDim.x) moba_gate_item(a, it, lds);
.LBB0_308:
	v_lshlrev_b32_e64 v1, v74, 1
	v_cmp_lt_i32_e32 vcc, -1, v74
	s_ashr_i32 s1, s0, 31
	v_lshlrev_b32_e64 v4, v3, 1
	v_cndmask_b32_e32 v1, 0, v1, vcc
	v_cmp_lt_i32_e32 vcc, -1, v3
	s_lshl_b64 s[0:1], s[0:1], 15
	v_readlane_b32 s6, v254, 30
	v_cndmask_b32_e32 v3, 0, v4, vcc
	v_lshlrev_b32_e64 v4, v2, 1
	v_cmp_lt_i32_e32 vcc, -1, v2
	s_add_u32 s0, s6, s0
	v_readlane_b32 s6, v254, 31
	v_lshl_or_b32 v1, 1, s26, v1
	v_cndmask_b32_e32 v2, 0, v4, vcc
	s_addc_u32 s1, s6, s1
	v_or3_b32 v1, v1, v3, v2
	v_lshl_add_u64 v[2:3], v[34:35], 2, s[0:1]
	global_store_dword v[2:3], v1, off
	s_barrier
	s_movk_i32 s0, 0x100
	s_waitcnt lgkmcnt(0)
	s_add_i32 s9, s0, s9

; __device__ __forceinline__ unsigned cvt_pk(float lo, float hi) { f32x2_t v = {lo, hi}; bf16x2_t b = __builtin_convertvector(v, bf16x2_t); return __builtin_bit_cast(unsigned, b); }
; __device__ __forceinline__ float sigmoidf_(float x) { return __builtin_amdgcn_rcpf(1.f + __builtin_amdgcn_exp2f(-1.4426950408889634f * x)); }
; template <int MODE>
; __device__ __forceinline__ void epi_scaled(Acc& acc, int pm, int pn, const float* ssq, const float* rq, const float* rkv, bf16_t* out, int ldo) {
;     ...
;     for (int ai = 0; ai < 2; ++ai)
; #pragma unroll
;         for (int m = 0; m < 4; ++m) {
;             const int row = pm * 256 + ai * 128 + t.wr * 64 + m * 16 + t.fr;
;             if (MODE == 1) rsv[ai][m] = (pn < 3) ? rq[row] : rkv[row];
;             else rsv[ai][m] = rstd_from_ssq(ssq, row);
;         }
; #pragma unroll
;     for (int ai = 0; ai < 2; ++ai)
; #pragma unroll
;         for (int m = 0; m < 4; ++m) {
;             int row = pm * 256 + ai * 128 + t.wr * 64 + m * 16 + t.fr;
;             const float rs = rsv[ai][m];
; #pragma unroll
;             for (int bj = 0; bj < 2; ++bj)
; #pragma unroll
;                 for (int n = 0; n < 2; ++n) {
;                     f32x4 v = acc[ai][bj][m][n] * rs;
;                     if (MODE == 2) {
; #pragma unroll
;                         for (int j = 0; j < 4; ++j) v[j] = sigmoidf_(v[j]);
;                     }
;                     u32x2 w; w[0] = cvt_pk(v[0], v[1]); w[1] = cvt_pk(v[2], v[3]);
;                     *(u32x2*)(out + (size_t)row * ldo + pn * 256 + bj * 128 + t.wc * 32 + n * 16 + t.fq * 4) = w;
;                 }
;         }
.LBB0_326:
	s_or_b64 exec, exec, s[36:37]
	v_mov_b32 v139, v179
	s_cmpk_lt_i32 s9, 0x60
	v_ashrrev_i32_e32 v1, 2, v139
	s_mov_b32 s8, 0x5890000
	v_and_b32_e32 v1, 0xffffffc0, v1
	v_and_or_b32 v130, v139, 15, s12
	s_cselect_b32 s8, s8, 0x5898000
	v_add_u32_e32 v148, v130, v1
	s_add_u32 s12, s16, s8
	s_addc_u32 s13, s17, 0
	v_ashrrev_i32_e32 v149, 31, v148
	v_lshl_add_u64 v[140:141], v[148:149], 2, s[12:13]
	global_load_dword v150, v[140:141], off
	global_load_dword v146, v[140:141], off offset:64
	global_load_dword v142, v[140:141], off offset:128
	global_load_dword v138, v[140:141], off offset:192
	global_load_dword v136, v[140:141], off offset:512
	global_load_dword v134, v[140:141], off offset:576
	global_load_dword v132, v[140:141], off offset:640
	global_load_dword v130, v[140:141], off offset:704
	s_lshl_b64 s[0:1], s[0:1], 1
	v_readlane_b32 s6, v254, 32
	v_readlane_b32 s7, v254, 33
	s_add_u32 s0, s6, s0
	s_addc_u32 s1, s7, s1
	v_lshrrev_b32_e32 v149, 1, v139
	v_and_b32_e32 v144, 0xc0, v139
	v_lshl_add_u64 v[140:141], s[0:1], 0, v[144:145]
	v_and_b32_e32 v144, 24, v149
	v_lshl_add_u64 v[140:141], v[140:141], 0, v[144:145]
	s_movk_i32 s8, 0xe00
	v_or_b32_e32 v143, 16, v148
	v_or_b32_e32 v147, 32, v148
	v_or_b32_e32 v137, 48, v148
	v_add_u32_e32 v135, 0x80, v148
	v_add_u32_e32 v133, 0x90, v148
	v_add_u32_e32 v131, 0xa0, v148
	v_add_u32_e32 v1, 0xb0, v148
	v_mad_i64_i32 v[148:149], s[0:1], v148, s8, v[140:141]
	s_waitcnt vmcnt(0)
	v_pk_mul_f32 v[116:117], v[116:117], v[150:151] op_sel_hi:[1,0]
	v_pk_mul_f32 v[114:115], v[114:115], v[150:151] op_sel_hi:[1,0]
	v_pk_mul_f32 v[100:101], v[100:101], v[146:147] op_sel_hi:[1,0]
	v_cvt_pk_bf16_f32 v114, v114, v115
	v_cvt_pk_bf16_f32 v115, v116, v117
	global_store_dwordx2 v[148:149], v[114:115], off offset:32
	v_pk_mul_f32 v[114:115], v[128:129], v[150:151] op_sel_hi:[1,0]
	v_pk_mul_f32 v[116:117], v[126:127], v[150:151] op_sel_hi:[1,0]
	v_pk_mul_f32 v[98:99], v[98:99], v[146:147] op_sel_hi:[1,0]
	v_cvt_pk_bf16_f32 v116, v116, v117
	v_cvt_pk_bf16_f32 v117, v114, v115
	global_store_dwordx2 v[148:149], v[116:117], off offset:256
	v_pk_mul_f32 v[114:115], v[124:125], v[150:151] op_sel_hi:[1,0]
	v_pk_mul_f32 v[116:117], v[122:123], v[150:151] op_sel_hi:[1,0]
	v_cvt_pk_bf16_f32 v98, v98, v99
	v_cvt_pk_bf16_f32 v116, v116, v117
	v_cvt_pk_bf16_f32 v117, v114, v115
	v_mad_i64_i32 v[114:115], s[0:1], v143, s8, v[140:141]
	v_cvt_pk_bf16_f32 v99, v100, v101
	global_store_dwordx2 v[114:115], v[98:99], off offset:32
	v_pk_mul_f32 v[98:99], v[112:113], v[146:147] op_sel_hi:[1,0]
	v_pk_mul_f32 v[100:101], v[110:111], v[146:147] op_sel_hi:[1,0]
	v_pk_mul_f32 v[84:85], v[84:85], v[142:143] op_sel_hi:[1,0]
	v_cvt_pk_bf16_f32 v100, v100, v101
	v_cvt_pk_bf16_f32 v101, v98, v99
	global_store_dwordx2 v[114:115], v[100:101], off offset:256
	v_pk_mul_f32 v[98:99], v[108:109], v[146:147] op_sel_hi:[1,0]
	v_pk_mul_f32 v[100:101], v[106:107], v[146:147] op_sel_hi:[1,0]
	v_pk_mul_f32 v[82:83], v[82:83], v[142:143] op_sel_hi:[1,0]
	v_cvt_pk_bf16_f32 v100, v100, v101
	v_cvt_pk_bf16_f32 v101, v98, v99
	v_mad_i64_i32 v[98:99], s[0:1], v147, s8, v[140:141]
	v_cvt_pk_bf16_f32 v82, v82, v83
	v_cvt_pk_bf16_f32 v83, v84, v85
	v_pk_mul_f32 v[52:53], v[52:53], v[138:139] op_sel_hi:[1,0]
	v_pk_mul_f32 v[50:51], v[50:51], v[138:139] op_sel_hi:[1,0]
	global_store_dwordx2 v[98:99], v[82:83], off offset:288
	v_mad_i64_i32 v[82:83], s[0:1], v137, s8, v[140:141]
	v_cvt_pk_bf16_f32 v50, v50, v51
	v_cvt_pk_bf16_f32 v51, v52, v53
	global_store_dwordx2 v[82:83], v[50:51], off offset:32
	v_pk_mul_f32 v[50:51], v[80:81], v[138:139] op_sel_hi:[1,0]
	v_pk_mul_f32 v[52:53], v[78:79], v[138:139] op_sel_hi:[1,0]
	v_pk_mul_f32 v[64:65], v[64:65], v[138:139] op_sel_hi:[1,0]
	v_cvt_pk_bf16_f32 v52, v52, v53
	v_cvt_pk_bf16_f32 v53, v50, v51
	v_pk_mul_f32 v[62:63], v[62:63], v[138:139] op_sel_hi:[1,0]
	global_store_dwordx2 v[82:83], v[52:53], off offset:256
	v_pk_mul_f32 v[50:51], v[68:69], v[138:139] op_sel_hi:[1,0]
	v_pk_mul_f32 v[52:53], v[66:67], v[138:139] op_sel_hi:[1,0]
	v_cvt_pk_bf16_f32 v62, v62, v63
	v_cvt_pk_bf16_f32 v63, v64, v65
	v_cvt_pk_bf16_f32 v52, v52, v53
	v_cvt_pk_bf16_f32 v53, v50, v51
	global_store_dwordx2 v[82:83], v[62:63], off
	global_store_dwordx2 v[82:83], v[52:53], off offset:288
	v_pk_mul_f32 v[52:53], v[72:73], v[136:137] op_sel_hi:[1,0]
	v_pk_mul_f32 v[62:63], v[70:71], v[136:137] op_sel_hi:[1,0]
	v_pk_mul_f32 v[54:55], v[54:55], v[136:137] op_sel_hi:[1,0]
	v_cvt_pk_bf16_f32 v62, v62, v63
	v_cvt_pk_bf16_f32 v63, v52, v53
	v_pk_mul_f32 v[52:53], v[56:57], v[136:137] op_sel_hi:[1,0]
	v_mad_i64_i32 v[50:51], s[0:1], v135, s8, v[140:141]
	v_cvt_pk_bf16_f32 v54, v54, v55
	v_cvt_pk_bf16_f32 v55, v52, v53
	global_store_dwordx2 v[50:51], v[54:55], off offset:32
	v_pk_mul_f32 v[52:53], v[76:77], v[136:137] op_sel_hi:[1,0]
	v_pk_mul_f32 v[54:55], v[74:75], v[136:137] op_sel_hi:[1,0]
; __device__ __forceinline__ unsigned cvt_pk(float lo, float hi) { f32x2_t v = {lo, hi}; bf16x2_t b = __builtin_convertvector(v, bf16x2_t); return __builtin_bit_cast(unsigned, b); }
; __device__ __forceinline__ float sigmoidf_(float x) { return __builtin_amdgcn_rcpf(1.f + __builtin_amdgcn_exp2f(-1.4426950408889634f * x)); }
; __device__ __forceinline__ int fresh_bid() { int t; asm volatile("s_mov_b32 %0, %1" : "=s"(t) : "s"(blockIdx.x)); return t; }
; #define ACC_ZERO(acc) _Pragma("unroll") for (int _a = 0; _a < 2; ++_a) _Pragma("unroll") for (int _b = 0; _b < 2; ++_b) _Pragma("unroll") for (int _m = 0; _m < 4; ++_m) \
;     _Pragma("unroll") for (int _n = 0; _n < 2; ++_n) acc[_a][_b][_m][_n] = (f32x4){0.f, 0.f, 0.f, 0.f}
; template <int MODE>
; __device__ __forceinline__ void epi_scaled(Acc& acc, int pm, int pn, const float* ssq, const float* rq, const float* rkv, bf16_t* out, int ldo) {
;     ...
;     for (int ai = 0; ai < 2; ++ai)
; #pragma unroll
;         for (int m = 0; m < 4; ++m) {
;             int row = pm * 256 + ai * 128 + t.wr * 64 + m * 16 + t.fr;
;             const float rs = rsv[ai][m];
; #pragma unroll
;             for (int bj = 0; bj < 2; ++bj)
; #pragma unroll
;                 for (int n = 0; n < 2; ++n) {
;                     f32x4 v = acc[ai][bj][m][n] * rs;
;                     if (MODE == 2) {
; #pragma unroll
;                         for (int j = 0; j < 4; ++j) v[j] = sigmoidf_(v[j]);
;                     }
;                     u32x2 w; w[0] = cvt_pk(v[0], v[1]); w[1] = cvt_pk(v[2], v[3]);
;                     *(u32x2*)(out + (size_t)row * ldo + pn * 256 + bj * 128 + t.wc * 32 + n * 16 + t.fq * 4) = w;
;                 }
;         }
; __device__ __forceinline__ void phase_mlaup(const Ctx& a, LAS unsigned char* lds) {
;     ...
;     for (int w = fresh_bid(); w < ntile; w += gridDim.x) {
;         int pm, pn; tile_of(w, nM, pm, pn);
;         Acc acc; ACC_ZERO(acc);
;         gemm_kloop(acc, pa, PA, W, 384, pm * 256, pn * 256, 384 / 64, lds);
;         epi_scaled<1>(acc, pm, pn, nullptr, rq, rkv, mr, MR);
;         __syncthreads();
	v_pk_mul_f32 v[36:37], v[36:37], v[134:135] op_sel_hi:[1,0]
	v_cvt_pk_bf16_f32 v54, v54, v55
	v_cvt_pk_bf16_f32 v55, v52, v53
	global_store_dwordx2 v[50:51], v[54:55], off offset:256
	v_pk_mul_f32 v[52:53], v[60:61], v[136:137] op_sel_hi:[1,0]
	v_pk_mul_f32 v[54:55], v[58:59], v[136:137] op_sel_hi:[1,0]
	v_pk_mul_f32 v[34:35], v[34:35], v[134:135] op_sel_hi:[1,0]
	v_cvt_pk_bf16_f32 v54, v54, v55
	v_cvt_pk_bf16_f32 v55, v52, v53
	global_store_dwordx2 v[50:51], v[62:63], off
	global_store_dwordx2 v[50:51], v[54:55], off offset:288
	v_mad_i64_i32 v[50:51], s[0:1], v133, s8, v[140:141]
	v_cvt_pk_bf16_f32 v34, v34, v35
	v_cvt_pk_bf16_f32 v35, v36, v37
	global_store_dwordx2 v[50:51], v[34:35], off offset:32
	v_pk_mul_f32 v[34:35], v[48:49], v[134:135] op_sel_hi:[1,0]
	v_pk_mul_f32 v[36:37], v[46:47], v[134:135] op_sel_hi:[1,0]
	v_pk_mul_f32 v[20:21], v[20:21], v[132:133] op_sel_hi:[1,0]
	v_cvt_pk_bf16_f32 v36, v36, v37
	v_cvt_pk_bf16_f32 v37, v34, v35
	global_store_dwordx2 v[50:51], v[36:37], off offset:256
	v_pk_mul_f32 v[34:35], v[40:41], v[134:135] op_sel_hi:[1,0]
	v_pk_mul_f32 v[36:37], v[38:39], v[134:135] op_sel_hi:[1,0]
	v_pk_mul_f32 v[18:19], v[18:19], v[132:133] op_sel_hi:[1,0]
	v_cvt_pk_bf16_f32 v36, v36, v37
	v_cvt_pk_bf16_f32 v37, v34, v35
	v_mad_i64_i32 v[34:35], s[0:1], v131, s8, v[140:141]
	v_cvt_pk_bf16_f32 v18, v18, v19
	v_cvt_pk_bf16_f32 v19, v20, v21
	global_store_dwordx2 v[34:35], v[18:19], off offset:32
	v_pk_mul_f32 v[18:19], v[32:33], v[132:133] op_sel_hi:[1,0]
	v_pk_mul_f32 v[20:21], v[30:31], v[132:133] op_sel_hi:[1,0]
	v_pk_mul_f32 v[4:5], v[4:5], v[130:131] op_sel_hi:[1,0]
	v_cvt_pk_bf16_f32 v20, v20, v21
	v_cvt_pk_bf16_f32 v21, v18, v19
	global_store_dwordx2 v[34:35], v[20:21], off offset:256
	v_pk_mul_f32 v[18:19], v[24:25], v[132:133] op_sel_hi:[1,0]
	v_pk_mul_f32 v[20:21], v[22:23], v[132:133] op_sel_hi:[1,0]
	v_pk_mul_f32 v[2:3], v[2:3], v[130:131] op_sel_hi:[1,0]
	v_cvt_pk_bf16_f32 v20, v20, v21
	v_cvt_pk_bf16_f32 v21, v18, v19
	v_mad_i64_i32 v[18:19], s[0:1], v1, s8, v[140:141]
	v_cvt_pk_bf16_f32 v2, v2, v3
	v_cvt_pk_bf16_f32 v3, v4, v5
	global_store_dwordx2 v[18:19], v[2:3], off offset:32
	v_pk_mul_f32 v[2:3], v[16:17], v[130:131] op_sel_hi:[1,0]
	v_pk_mul_f32 v[4:5], v[14:15], v[130:131] op_sel_hi:[1,0]
	v_pk_mul_f32 v[120:121], v[120:121], v[150:151] op_sel_hi:[1,0]
	v_cvt_pk_bf16_f32 v4, v4, v5
	v_cvt_pk_bf16_f32 v5, v2, v3
	v_pk_mul_f32 v[118:119], v[118:119], v[150:151] op_sel_hi:[1,0]
	v_pk_mul_f32 v[104:105], v[104:105], v[146:147] op_sel_hi:[1,0]
	v_pk_mul_f32 v[102:103], v[102:103], v[146:147] op_sel_hi:[1,0]
	v_pk_mul_f32 v[96:97], v[96:97], v[142:143] op_sel_hi:[1,0]
	v_pk_mul_f32 v[94:95], v[94:95], v[142:143] op_sel_hi:[1,0]
	v_pk_mul_f32 v[92:93], v[92:93], v[142:143] op_sel_hi:[1,0]
	v_pk_mul_f32 v[90:91], v[90:91], v[142:143] op_sel_hi:[1,0]
	v_pk_mul_f32 v[88:89], v[88:89], v[142:143] op_sel_hi:[1,0]
	v_pk_mul_f32 v[86:87], v[86:87], v[142:143] op_sel_hi:[1,0]
	v_pk_mul_f32 v[44:45], v[44:45], v[134:135] op_sel_hi:[1,0]
	v_pk_mul_f32 v[42:43], v[42:43], v[134:135] op_sel_hi:[1,0]
	v_pk_mul_f32 v[28:29], v[28:29], v[132:133] op_sel_hi:[1,0]
	v_pk_mul_f32 v[26:27], v[26:27], v[132:133] op_sel_hi:[1,0]
	v_pk_mul_f32 v[12:13], v[12:13], v[130:131] op_sel_hi:[1,0]
	v_pk_mul_f32 v[10:11], v[10:11], v[130:131] op_sel_hi:[1,0]
	global_store_dwordx2 v[18:19], v[4:5], off offset:256
	v_pk_mul_f32 v[2:3], v[8:9], v[130:131] op_sel_hi:[1,0]
	v_pk_mul_f32 v[4:5], v[6:7], v[130:131] op_sel_hi:[1,0]
	v_cvt_pk_bf16_f32 v118, v118, v119
	v_cvt_pk_bf16_f32 v119, v120, v121
	v_cvt_pk_bf16_f32 v102, v102, v103
	v_cvt_pk_bf16_f32 v103, v104, v105
	v_cvt_pk_bf16_f32 v94, v94, v95
	v_cvt_pk_bf16_f32 v95, v96, v97
	v_cvt_pk_bf16_f32 v90, v90, v91
	v_cvt_pk_bf16_f32 v91, v92, v93
	v_cvt_pk_bf16_f32 v86, v86, v87
	v_cvt_pk_bf16_f32 v87, v88, v89
	v_cvt_pk_bf16_f32 v42, v42, v43
	v_cvt_pk_bf16_f32 v43, v44, v45
	v_cvt_pk_bf16_f32 v26, v26, v27
	v_cvt_pk_bf16_f32 v27, v28, v29
	v_cvt_pk_bf16_f32 v10, v10, v11
	v_cvt_pk_bf16_f32 v11, v12, v13
	v_cvt_pk_bf16_f32 v4, v4, v5
	v_cvt_pk_bf16_f32 v5, v2, v3
	global_store_dwordx2 v[148:149], v[118:119], off
	global_store_dwordx2 v[148:149], v[116:117], off offset:288
	global_store_dwordx2 v[114:115], v[102:103], off
	global_store_dwordx2 v[114:115], v[100:101], off offset:288
	global_store_dwordx2 v[98:99], v[94:95], off
	global_store_dwordx2 v[98:99], v[90:91], off offset:32
	global_store_dwordx2 v[98:99], v[86:87], off offset:256
	global_store_dwordx2 v[50:51], v[42:43], off
	global_store_dwordx2 v[50:51], v[36:37], off offset:288
	global_store_dwordx2 v[34:35], v[26:27], off
	global_store_dwordx2 v[34:35], v[20:21], off offset:288
	global_store_dwordx2 v[18:19], v[10:11], off
	global_store_dwordx2 v[18:19], v[4:5], off offset:288
	s_barrier
	s_movk_i32 s0, 0x100
	s_waitcnt lgkmcnt(0)
	s_add_i32 s9, s0, s9
	s_cmpk_lt_i32 s9, 0xe0
	s_cbranch_scc0 .LBB0_325

; __device__ __forceinline__ float bf2f(bf16_t h) { return __uint_as_float(((unsigned)h) << 16); }
; __device__ __forceinline__ int fresh_tid() { int t; asm volatile("v_mov_b32 %0, %1" : "=v"(t) : "v"(threadIdx.x)); return t; }
; __device__ __forceinline__ int fresh_bid() { int t; asm volatile("s_mov_b32 %0, %1" : "=s"(t) : "s"(blockIdx.x)); return t; }
; __device__ __forceinline__ void kmean_items(const Ctx& a, LAS unsigned char* lds) {
;     ...
;     for (int it = fresh_bid(); it < 256; it += gridDim.x) {
;         int hh = it >> 5, n = it & 31, d = fresh_tid() & 63, tg = fresh_tid() >> 6;
;         float s = 0.f;
;         for (int i = 0; i < 32; ++i) s += bf2f(pa[(size_t)(n * 256 + tg * 32 + i) * PA + C_MK + hh * 64 + d]);
;         part[tg * 64 + d] = s;
;         __syncthreads();
;         if (fresh_tid() < 64) {
;             float tsum = 0.f;
; #pragma unroll
;             for (int g2 = 0; g2 < 8; ++g2) tsum += part[g2 * 64 + d];
;             kmean[(size_t)it * 64 + d] = tsum * (1.f / 256.f);
;         }
;         __syncthreads();
;     }
.LBB0_331:
	s_or_b64 exec, exec, s[12:13]
	s_barrier
	s_movk_i32 s1, 0x100
	s_waitcnt lgkmcnt(0)
	s_add_i32 s0, s1, s0

; __device__ __forceinline__ int fresh_bid() { int t; asm volatile("s_mov_b32 %0, %1" : "=s"(t) : "s"(blockIdx.x)); return t; }
; __device__ __forceinline__ void gdn_intra_item(const Ctx& a, int l, int h, int c, LAS unsigned char* lds) {
;     ...
;         if (u == 0) ((float*)(a.ws + WS_GLAST))[h * 128 + c] = gl;
;     }
;     __syncthreads();
; __global__ void __launch_bounds__(NT, 2) mk_fwd(Args a_in) {
;     ...
;                 for (int it = fresh_bid(); it < 512; it += gridDim.x) gdn_intra_item(a, l, it & 3, it >> 2, lds);
.LBB0_339:
	s_or_b64 exec, exec, s[12:13]
	s_waitcnt lgkmcnt(0)
	s_barrier
	s_movk_i32 s0, 0x100
	s_waitcnt lgkmcnt(0)
	s_add_i32 s9, s0, s9

; #define LAS __attribute__((address_space(3)))
; __device__ __forceinline__ float lo_bf(unsigned u) { return __uint_as_float(u << 16); }
; __device__ __forceinline__ float hi_bf(unsigned u) { return __uint_as_float(u & 0xffff0000u); }
; __device__ __forceinline__ int fresh_tid() { int t; asm volatile("v_mov_b32 %0, %1" : "=v"(t) : "v"(threadIdx.x)); return t; }
; __device__ __forceinline__ int fresh_bid() { int t; asm volatile("s_mov_b32 %0, %1" : "=s"(t) : "s"(blockIdx.x)); return t; }
; __device__ __forceinline__ void phase_post1(const Ctx& a, int l, LAS unsigned char* lds) {
;     bf16_t* pa = (bf16_t*)(a.ws + B_PROJ); float* rq = (float*)(a.ws + WS_RQ); float* rkv = (float*)(a.ws + WS_RKV);
;     const float2* t64 = (const float2*)(a.ws + WS_TAB64);
;     const float* gq = a.in(I_MQN) + l * 64; const float* gk = a.in(I_MKN) + l * 64;
;     const int lane = fresh_tid() & 63, wv = fresh_tid() >> 6;
;     for (int tk = fresh_bid() * 8 + wv; tk < SEQ; tk += gridDim.x * 8) {
;         bf16_t* pr = pa + (size_t)tk * PA;
;         u32x2 cq = *(const u32x2*)(pr + C_CQ + lane * 4);
;         float s1 = lo_bf(cq[0]) * lo_bf(cq[0]) + hi_bf(cq[0]) * hi_bf(cq[0]) + lo_bf(cq[1]) * lo_bf(cq[1]) + hi_bf(cq[1]) * hi_bf(cq[1]);
;         unsigned ck = *(const unsigned*)(pr + C_CKV + lane * 2);
;         float s2 = lo_bf(ck) * lo_bf(ck) + hi_bf(ck) * hi_bf(ck);
;         s1 = wave_sum(s1); s2 = wave_sum(s2);
;         if (lane == 0) { rq[tk] = rsqrtf(s1 * (1.f / 256.f) + EPS); rkv[tk] = rsqrtf(s2 * (1.f / 128.f) + EPS); }
.LBB0_518:
	v_readlane_b32 s0, v254, 48
	v_readlane_b32 s1, v254, 49
	s_waitcnt lgkmcnt(0)
	s_nop 3
	global_load_dwordx4 v[2:5], v145, s[0:1]
	s_waitcnt vmcnt(0)
	v_mov_b32 v8, v179
	v_mov_b32 v1, v179
	s_mov_b32 s0, s2
	s_movk_i32 s1, 0x2000
	v_ashrrev_i32_e32 v7, 6, v1
	v_lshl_add_u32 v6, s0, 3, v7
	v_cmp_gt_i32_e32 vcc, s1, v6
	s_and_saveexec_b64 s[12:13], vcc
	s_cbranch_execz .LBB0_523
	v_and_b32_e32 v1, 64, v195
	v_add_u32_e32 v11, 64, v1
	v_xor_b32_e32 v1, 32, v195
	v_cmp_lt_i32_e32 vcc, v1, v11
	v_xor_b32_e32 v13, 16, v195
	s_movk_i32 s1, 0x100
	v_cndmask_b32_e32 v1, v195, v1, vcc
	v_cmp_lt_i32_e32 vcc, v13, v11
	v_and_b32_e32 v9, 63, v8
	v_lshlrev_b32_e32 v12, 1, v9
	v_cndmask_b32_e32 v13, v195, v13, vcc
	v_lshlrev_b32_e32 v48, 2, v13
	v_xor_b32_e32 v13, 8, v195
	v_cmp_lt_i32_e32 vcc, v13, v11
	v_readlane_b32 s6, v255, 19
	v_and_b32_e32 v14, 31, v8
	v_cndmask_b32_e32 v13, v195, v13, vcc
	v_lshlrev_b32_e32 v49, 2, v13
	v_xor_b32_e32 v13, 4, v195
	v_cmp_lt_i32_e32 vcc, v13, v11
	v_and_b32_e32 v16, 64, v12
	v_readlane_b32 s7, v255, 20
	v_cndmask_b32_e32 v13, v195, v13, vcc
	v_lshlrev_b32_e32 v50, 2, v13
	v_xor_b32_e32 v13, 2, v195
	v_cmp_lt_i32_e32 vcc, v13, v11
	v_lshlrev_b32_e32 v7, 5, v7
	v_lshlrev_b32_e32 v10, 2, v9
	v_cndmask_b32_e32 v13, v195, v13, vcc
	v_lshlrev_b32_e32 v51, 2, v13
	v_xor_b32_e32 v13, 1, v195
	v_cmp_lt_i32_e32 vcc, v13, v11
	v_or_b32_e32 v18, 0x80, v16
	v_or_b32_e32 v20, 0x100, v16
	v_cndmask_b32_e32 v11, v195, v13, vcc
	v_or_b32_e32 v22, 0x180, v16
	v_or_b32_e32 v24, 0x200, v16
	v_or_b32_e32 v26, 0x280, v16
	v_or_b32_e32 v28, 0x300, v16
	v_or_b32_e32 v30, 0x380, v16
	v_lshl_add_u64 v[2:3], v[2:3], 0, s[6:7]
	v_lshlrev_b32_e32 v144, 2, v14
	v_lshl_add_u64 v[4:5], v[4:5], 0, s[6:7]
	v_lshl_add_u32 v7, s0, 8, v7
	v_lshlrev_b32_e32 v1, 2, v1
	v_lshlrev_b32_e32 v52, 2, v11
	v_cmp_eq_u32_e32 vcc, 0, v9
	s_waitcnt lgkmcnt(0)
	s_lshl_b32 s9, s1, 3
	v_lshl_add_u64 v[2:3], v[2:3], 0, v[144:145]
	v_lshl_add_u64 v[4:5], v[4:5], 0, v[144:145]
	v_or_b32_e32 v8, v7, v14
	s_lshl_b32 s26, s1, 8
	s_mov_b64 s[38:39], 0
	v_lshlrev_b32_e32 v144, 1, v10
	v_lshlrev_b32_e32 v10, 1, v12
	v_lshlrev_b32_e32 v12, 1, v14
	v_lshlrev_b32_e32 v14, 1, v16
	v_lshlrev_b32_e32 v16, 1, v18
	v_lshlrev_b32_e32 v18, 1, v20
	v_lshlrev_b32_e32 v20, 1, v22
	v_lshlrev_b32_e32 v22, 1, v24
	v_lshlrev_b32_e32 v24, 1, v26
	v_lshlrev_b32_e32 v26, 1, v28
	v_lshlrev_b32_e32 v28, 1, v30
	s_branch .LBB0_521

; __device__ __forceinline__ float lo_bf(unsigned u) { return __uint_as_float(u << 16); }
; __device__ __forceinline__ float hi_bf(unsigned u) { return __uint_as_float(u & 0xffff0000u); }
; __device__ __forceinline__ int fresh_tid() { int t; asm volatile("v_mov_b32 %0, %1" : "=v"(t) : "v"(threadIdx.x)); return t; }
; __device__ __forceinline__ int fresh_bid() { int t; asm volatile("s_mov_b32 %0, %1" : "=s"(t) : "s"(blockIdx.x)); return t; }
; __device__ __forceinline__ void phase_gdnpost(const Ctx& a, int l, int b) {
;     const bf16_t* pa = (const bf16_t*)(a.ws + B_PROJ); bf16_t* br = (bf16_t*)(a.ws + B_BRANCH);
;     const float* onorm = a.in(I_ONORM) + l * 128;
;     const int tid = fresh_tid(), lane = tid & 63, wv = tid >> 6;
;     float g[8];
; #pragma unroll
;     for (int e = 0; e < 8; ++e) g[e] = onorm[(lane & 15) * 8 + e];
;     for (int tk = fresh_bid() * 8 + wv; tk < SEQ; tk += gridDim.x * 8) {
;         bf16_t* op = br + ((size_t)b * SEQ + tk) * BR + 512 + lane * 8;
;         u32x4 ov = *(const u32x4*)op;
;         u32x4 zv = *(const u32x4*)(pa + (size_t)tk * PA + C_GZ + lane * 8);
;         float x[8]; float ss = 0.f;
; #pragma unroll
;         for (int e = 0; e < 4; ++e) { x[2 * e] = lo_bf(ov[e]); x[2 * e + 1] = hi_bf(ov[e]); ss += x[2 * e] * x[2 * e] + x[2 * e + 1] * x[2 * e + 1]; }
;         ss += __shfl_xor(ss, 1); ss += __shfl_xor(ss, 2); ss += __shfl_xor(ss, 4); ss += __shfl_xor(ss, 8);
.LBB0_526:
	s_and_b64 vcc, exec, s[92:93]
	s_cbranch_vccz .LBB0_531
	v_readlane_b32 s0, v255, 3
	v_readlane_b32 s1, v255, 4
	s_waitcnt lgkmcnt(0)
	s_nop 3
	global_load_dwordx2 v[2:3], v145, s[0:1]
	v_readlane_b32 s0, v253, 61
	v_readlane_b32 s1, v253, 62
	s_lshl_b64 s[0:1], s[0:1], 2
	v_mov_b32 v1, v179
	s_waitcnt vmcnt(0)
	v_lshlrev_b32_e32 v4, 5, v1
	v_and_b32_e32 v144, 0x1e0, v4
	v_ashrrev_i32_e32 v10, 6, v1
	v_lshl_add_u64 v[2:3], v[2:3], 0, s[0:1]
	v_lshl_add_u64 v[6:7], v[2:3], 0, v[144:145]
	flat_load_dwordx4 v[2:5], v[6:7]
	s_nop 0
	flat_load_dwordx4 v[6:9], v[6:7] offset:16
	s_mov_b32 s0, s2
	s_nop 0
	v_lshl_add_u32 v10, s0, 3, v10
	s_movk_i32 s0, 0x2000
	v_cmp_gt_i32_e32 vcc, s0, v10
	s_and_saveexec_b64 s[0:1], vcc
	v_readlane_b32 s6, v255, 7
	s_movk_i32 s26, 0x1fff
	v_readlane_b32 s7, v255, 8
	s_cbranch_execz .LBB0_530
	v_lshlrev_b32_e32 v1, 3, v1
	v_and_b32_e32 v11, 64, v195
	v_and_b32_e32 v16, 0x1f8, v1
	v_xor_b32_e32 v1, 1, v195
	v_add_u32_e32 v11, 64, v11
	v_cmp_lt_i32_e32 vcc, v1, v11
	v_xor_b32_e32 v12, 2, v195
	s_movk_i32 s8, 0x100
	v_cndmask_b32_e32 v1, v195, v1, vcc
	v_cmp_lt_i32_e32 vcc, v12, v11
	v_xor_b32_e32 v13, 4, v195
	v_xor_b32_e32 v14, 8, v195
	v_cndmask_b32_e32 v12, v195, v12, vcc
	v_cmp_lt_i32_e32 vcc, v13, v11
	v_lshlrev_b32_e32 v1, 2, v1
	v_lshlrev_b32_e32 v12, 2, v12
	v_cndmask_b32_e32 v13, v195, v13, vcc
	v_cmp_lt_i32_e32 vcc, v14, v11
	v_lshlrev_b32_e32 v13, 2, v13
	s_waitcnt lgkmcnt(0)
	s_lshl_b32 s9, s8, 3
	v_cndmask_b32_e32 v11, v195, v14, vcc
	v_lshlrev_b32_e32 v14, 2, v11
	s_mov_b64 s[12:13], 0
	v_lshlrev_b32_e32 v144, 1, v16

; #define LAS __attribute__((address_space(3)))
; __device__ __forceinline__ int fresh_tid() { int t; asm volatile("v_mov_b32 %0, %1" : "=v"(t) : "v"(threadIdx.x)); return t; }
; __device__ __forceinline__ int fresh_bid() { int t; asm volatile("s_mov_b32 %0, %1" : "=s"(t) : "s"(blockIdx.x)); return t; }
; #define ACC_ZERO(acc) _Pragma("unroll") for (int _a = 0; _a < 2; ++_a) _Pragma("unroll") for (int _b = 0; _b < 2; ++_b) _Pragma("unroll") for (int _m = 0; _m < 4; ++_m) \
;     _Pragma("unroll") for (int _n = 0; _n < 2; ++_n) acc[_a][_b][_m][_n] = (f32x4){0.f, 0.f, 0.f, 0.f}
; __device__ __forceinline__ void gemm_stage_first(const bf16_t* __restrict__ A, int lda, const bf16_t* __restrict__ Bt, int ldb, int brow, int bcol, LAS unsigned char* lds) {
;     const int tid = fresh_tid();
;     const int wvu = __builtin_amdgcn_readfirstlane(tid >> 6);
;     unsigned offA, offB;
;     { int _r, _c; stage_rc(tid * 16, _r, _c); offA = (unsigned)(_r * lda + _c) * 2u; offB = (unsigned)(_r * ldb + _c) * 2u; }
;     STAGE(SBo(0, 0), Bt, ldb, bcol, 0, offB); STAGE(SAo(0, 0), A, lda, brow, 0, offA);
;     STAGE(SBo(0, 1), Bt, ldb, bcol + HALF, 0, offB); STAGE(SAo(0, 1), A, lda, brow + HALF, 0, offA);
; }
; __device__ __forceinline__ void phase_proj(const Ctx& a, int b, LAS unsigned char* lds) {
;     ...
;     for (int w = fresh_bid(); w < ntile; w += gridDim.x) {
;         int pm, pn; tile_of(w, nM, pm, pn);
;         Acc acc; ACC_ZERO(acc);
;         gemm_kloop<true>(acc, xb, DM, W, DM, pm * 256, pn * 256, DM / 64, lds);
;         { const int wn = w + (int)gridDim.x; if (wn < ntile) { int pm2, pn2; tile_of(wn, nM, pm2, pn2); gemm_stage_first(xb, DM, W, DM, pm2 * 256, pn2 * 256, lds); } }
.LBB0_546:
	s_or_b64 exec, exec, s[36:37]
	s_movk_i32 s1, 0x100
	s_waitcnt lgkmcnt(0)
	s_add_i32 s9, s1, s9
	s_cmpk_gt_i32 s9, 0x1ff
	s_cselect_b64 s[36:37], -1, 0
	s_and_b64 vcc, exec, s[36:37]
	s_cbranch_vccnz .LBB0_539
	s_ashr_i32 s1, s9, 31
	s_lshr_b32 s1, s1, 27
	s_add_i32 s1, s9, s1
	v_mov_b32 v1, v179
	s_and_b32 s8, s1, 0xffffe0
	v_ashrrev_i32_e32 v131, 31, v1
	s_lshl_b32 s1, s1, 3
	v_lshrrev_b32_e32 v131, 26, v131
	s_and_b32 s40, s1, 0xffffff00
	v_readfirstlane_b32 s1, v1
	v_lshlrev_b32_e32 v130, 4, v1
	v_add_u32_e32 v131, v1, v131
	v_bfe_i32 v1, v1, 27, 1
	v_lshrrev_b32_e32 v1, 22, v1
	v_add_u32_e32 v1, v130, v1
	v_and_b32_e32 v1, 0xfffffc00, v1
	v_sub_u32_e32 v1, v130, v1
	v_lshrrev_b32_e32 v130, 4, v1
	v_bitop3_b32 v130, v130, v1, 32 bitop3:0x6c
	v_ashrrev_i32_e32 v1, 31, v1
	v_lshrrev_b32_e32 v1, 26, v1
	v_add_u32_e32 v1, v130, v1
	s_sub_i32 s8, s9, s8
	s_ashr_i32 s1, s1, 6
	v_ashrrev_i32_e32 v1, 6, v1
	s_lshl_b32 s38, s8, 8
	v_ashrrev_i32_e32 v131, 6, v131
	v_mul_i32_i24_e32 v133, 64, v1
	s_mov_b32 s8, s1
	s_mov_b32 s42, s27
	v_lshlrev_b32_e32 v132, 3, v131
	v_lshlrev_b32_e32 v131, 5, v131
	v_sub_u32_e32 v130, v130, v133
	s_ashr_i32 s43, s42, 31
	v_and_b32_e32 v132, 0x1ffff0, v132
	v_and_b32_e32 v131, 32, v131
	v_ashrrev_i16_sdwa v130, v194, sext(v130) dst_sel:DWORD dst_unused:UNUSED_PAD src0_sel:DWORD src1_sel:BYTE_0
	s_lshl_b64 s[42:43], s[42:43], 7
	v_add_u32_sdwa v130, v131, sext(v130) dst_sel:DWORD dst_unused:UNUSED_PAD src0_sel:DWORD src1_sel:WORD_0
	v_add_lshl_u32 v1, v1, v132, 11
	s_add_u32 s42, s86, s42
	v_lshl_add_u32 v144, v130, 1, v1
	s_addc_u32 s43, s87, s43
	s_ashr_i32 s41, s40, 31
	v_lshl_add_u64 v[130:131], s[42:43], 0, v[144:145]
	s_lshl_b64 s[42:43], s[40:41], 11
	s_lshl_b32 s8, s8, 10
	v_lshl_add_u64 v[132:133], v[130:131], 0, s[42:43]
	s_or_b32 s42, s40, 64
	s_add_i32 s8, s8, 0
	s_ashr_i32 s43, s42, 31
	s_add_i32 m0, s8, 0x10000
	s_lshl_b64 s[42:43], s[42:43], 11
	global_load_lds_dwordx4 v[132:133], off
	v_lshl_add_u64 v[130:131], v[130:131], 0, s[42:43]
	s_add_i32 m0, s8, 0x12000
	s_mov_b32 s8, s1
	s_mov_b32 s42, s27
	global_load_lds_dwordx4 v[130:131], off
	s_ashr_i32 s43, s42, 31
	s_lshl_b64 s[42:43], s[42:43], 7
	v_readlane_b32 s6, v254, 54
	v_readlane_b32 s7, v254, 55
	s_add_u32 s42, s6, s42
	s_addc_u32 s43, s7, s43
	s_ashr_i32 s39, s38, 31
	v_lshl_add_u64 v[130:131], s[42:43], 0, v[144:145]
	s_lshl_b64 s[42:43], s[38:39], 11
	s_lshl_b32 s8, s8, 10
	v_lshl_add_u64 v[132:133], v[130:131], 0, s[42:43]
	s_or_b32 s42, s38, 64
	s_add_i32 s8, s8, 0
	s_ashr_i32 s43, s42, 31
	s_mov_b32 m0, s8
	s_lshl_b64 s[42:43], s[42:43], 11
	global_load_lds_dwordx4 v[132:133], off
	v_lshl_add_u64 v[130:131], v[130:131], 0, s[42:43]
	s_add_i32 m0, s8, 0x2000
	s_mov_b32 s8, s1
	s_mov_b32 s42, s27
	global_load_lds_dwordx4 v[130:131], off
	s_ashr_i32 s43, s42, 31
	s_or_b32 s44, s40, 0x80
	s_lshl_b64 s[42:43], s[42:43], 7
	s_add_u32 s42, s86, s42
	s_addc_u32 s43, s87, s43
	s_lshl_b32 s8, s8, 10
	s_ashr_i32 s45, s44, 31
	s_or_b32 s40, s40, 0xc0
	v_lshl_add_u64 v[130:131], s[42:43], 0, v[144:145]
	s_add_i32 s8, s8, 0
	s_lshl_b64 s[42:43], s[44:45], 11
	s_ashr_i32 s41, s40, 31
	s_add_i32 m0, s8, 0x14000
	v_lshl_add_u64 v[132:133], v[130:131], 0, s[42:43]
	s_lshl_b64 s[40:41], s[40:41], 11
	global_load_lds_dwordx4 v[132:133], off
	v_lshl_add_u64 v[130:131], v[130:131], 0, s[40:41]
	s_add_i32 m0, s8, 0x16000
	s_mov_b32 s40, s27
	global_load_lds_dwordx4 v[130:131], off
	s_ashr_i32 s41, s40, 31
	s_or_b32 s42, s38, 0x80
	s_lshl_b64 s[40:41], s[40:41], 7
	s_add_u32 s40, s6, s40
	s_addc_u32 s41, s7, s41
	s_lshl_b32 s1, s1, 10
	s_ashr_i32 s43, s42, 31
	s_or_b32 s38, s38, 0xc0
	v_lshl_add_u64 v[130:131], s[40:41], 0, v[144:145]
	s_add_i32 s1, s1, 0
	s_lshl_b64 s[40:41], s[42:43], 11
	s_ashr_i32 s39, s38, 31
	s_add_i32 m0, s1, 0x4000
	v_lshl_add_u64 v[132:133], v[130:131], 0, s[40:41]
	s_lshl_b64 s[38:39], s[38:39], 11
	global_load_lds_dwordx4 v[132:133], off
	v_lshl_add_u64 v[130:131], v[130:131], 0, s[38:39]
	s_add_i32 m0, s1, 0x6000
	s_nop 0
	global_load_lds_dwordx4 v[130:131], off
	s_branch .LBB0_539
.LBB0_548:
	s_barrier
	s_movk_i32 s0, 0x100
	s_waitcnt lgkmcnt(0)
	s_add_i32 s26, s0, s26

; __device__ __forceinline__ int fresh_bid() { int t; asm volatile("s_mov_b32 %0, %1" : "=s"(t) : "s"(blockIdx.x)); return t; }
; __device__ __forceinline__ void phase_convert(const Ctx& a, int l, LAS unsigned char* lds) {
;     ...
;     for (int j = 0; j < 10; ++j) {
;         CJob c = get_job(j, a, l);
;         const int nkt = c.K / 64, nnt = c.Ntot / 64, ntile = nkt * nnt;
;         int first = (int)((fresh_bid() + gridDim.x - (base % gridDim.x)) % gridDim.x);
;         float pv[8];
;     ...
;         if (first < ntile) CV_LOAD(first);
.LBB0_717:
	s_mov_b32 s30, s2
	s_movk_i32 s9, 0x100
	s_mul_i32 s46, s26, s51
	s_add_i32 s52, s46, 5
	s_mul_hi_u32 s52, s52, 0x2aaaaaab
	v_cvt_f32_u32_e32 v22, s51
	s_waitcnt lgkmcnt(0)
	v_cvt_f32_u32_e32 v21, s9
	s_sub_i32 s26, 0, s9
	v_rcp_iflag_f32_e32 v21, v21
	s_nop 0
	v_mul_f32_e32 v21, 0x4f7ffffe, v21
	v_cvt_u32_f32_e32 v23, v21
	v_rcp_iflag_f32_e32 v21, v22
	v_readfirstlane_b32 s42, v23
	s_mul_i32 s26, s26, s42
	s_mul_hi_u32 s26, s42, s26
	s_add_i32 s42, s42, s26
	s_mul_hi_u32 s26, s48, s42
	s_mul_i32 s26, s26, s9
	s_sub_i32 s26, s48, s26
	s_sub_i32 s43, s26, s9
	s_cmp_ge_u32 s26, s9
	s_cselect_b32 s26, s43, s26
	s_sub_i32 s43, s26, s9
	s_cmp_ge_u32 s26, s9
	s_cselect_b32 s26, s43, s26
	s_add_i32 s30, s9, s30
	s_sub_i32 s26, s30, s26
	s_mul_hi_u32 s30, s26, s42
	s_mul_i32 s30, s30, s9
	s_sub_i32 s26, s26, s30
	s_sub_i32 s30, s26, s9
	s_cmp_ge_u32 s26, s9
	s_cselect_b32 s26, s30, s26
	s_sub_i32 s30, s26, s9
	s_cmp_ge_u32 s26, s9
	s_cselect_b32 s53, s30, s26
	s_cmp_lt_i32 s53, s52
	s_cselect_b64 s[44:45], -1, 0
	s_cmp_ge_i32 s53, s52
	s_cbranch_scc1 .LBB0_693
	s_waitcnt vmcnt(0) lgkmcnt(0)
	v_mul_f32_e32 v21, 0x4f7ffffe, v21
	v_cvt_u32_f32_e32 v21, v21
	s_sub_i32 s26, 0, s51
	v_readfirstlane_b32 s44, v21
	v_readfirstlane_b32 s56, v14
	v_readfirstlane_b32 s57, v15
	v_readfirstlane_b32 s58, v16
	v_readfirstlane_b32 s59, v17
	s_xor_b64 s[42:43], s[36:37], -1
	v_cmp_ne_u64_e64 s[36:37], 0, v[16:17]
	s_nop 3
	s_mul_i32 s26, s26, s44
	s_mul_hi_u32 s26, s44, s26
	s_add_i32 s54, s44, s26
	s_lshl_b64 s[44:45], s[40:41], 1
	s_add_u32 s38, s38, s44
	s_addc_u32 s39, s39, s45
	s_lshl_b64 s[40:41], s[0:1], 5
	v_lshlrev_b32_e32 v141, 2, v2
	v_add_u32_e32 v32, 0x10400, v20
	v_mov_b32_e32 v42, 1.0
	v_mov_b32_e32 v43, 1.0
	v_mov_b32_e32 v44, 1.0
	v_mov_b32_e32 v45, 1.0
	v_mov_b32_e32 v46, 1.0
	v_mov_b32_e32 v47, 1.0
	v_mov_b32_e32 v48, 1.0
	v_mov_b32_e32 v49, 1.0
	v_mov_b32_e32 v58, 1.0
	v_mov_b32_e32 v59, 1.0
	v_mov_b32_e32 v60, 1.0
	v_mov_b32_e32 v61, 1.0
	v_mov_b32_e32 v62, 1.0
	v_mov_b32_e32 v63, 1.0
	v_mov_b32_e32 v64, 1.0
	v_mov_b32_e32 v65, 1.0
	v_mov_b32_e32 v74, 1.0
	v_mov_b32_e32 v75, 1.0
	v_mov_b32_e32 v76, 1.0
	v_mov_b32_e32 v77, 1.0
	v_mov_b32_e32 v78, 1.0
	v_mov_b32_e32 v79, 1.0
	v_mov_b32_e32 v80, 1.0
	v_mov_b32_e32 v81, 1.0
	v_mov_b32_e32 v90, 1.0
	v_mov_b32_e32 v91, 1.0
	v_mov_b32_e32 v92, 1.0
	v_mov_b32_e32 v93, 1.0
	v_mov_b32_e32 v94, 1.0
	v_mov_b32_e32 v95, 1.0
	v_mov_b32_e32 v96, 1.0
	v_mov_b32_e32 v97, 1.0
	v_mov_b32_e32 v106, 1.0
	v_mov_b32_e32 v107, 1.0
	v_mov_b32_e32 v108, 1.0
	v_mov_b32_e32 v109, 1.0
	v_mov_b32_e32 v110, 1.0
	v_mov_b32_e32 v111, 1.0
	v_mov_b32_e32 v112, 1.0
	v_mov_b32_e32 v113, 1.0
	v_mov_b32_e32 v122, 1.0
	v_mov_b32_e32 v123, 1.0
	v_mov_b32_e32 v124, 1.0
	v_mov_b32_e32 v125, 1.0
	v_mov_b32_e32 v126, 1.0
	v_mov_b32_e32 v127, 1.0
	v_mov_b32_e32 v128, 1.0
	v_mov_b32_e32 v129, 1.0
	s_mov_b32 s60, 0
	s_mul_i32 s30, s53, 6
	s_cmp_ge_i32 s30, s46
	s_cbranch_scc1 .Lcv_isd_a
	s_mul_hi_u32 s26, s30, s54
	s_mul_i32 s55, s26, s51
	s_sub_i32 s55, s30, s55
	s_sub_i32 s61, s55, s51
	s_add_i32 s62, s26, 1
	s_cmp_ge_u32 s55, s51
	s_cselect_b32 s26, s62, s26
	s_cselect_b32 s55, s61, s55
	s_sub_i32 s61, s55, s51
	s_add_i32 s62, s26, 1
	s_cmp_ge_u32 s55, s51
	s_cselect_b32 s26, s62, s26
	s_cselect_b32 s55, s61, s55
	s_lshl_b32 s61, s26, 6
	s_lshl_b32 s62, s55, 6
	v_add_u32_e32 v130, s62, v1
	s_add_i32 s44, s50, -1
	v_min_u32_e32 v136, s44, v130
	v_add_u32_e32 v137, s61, v2
	v_mad_u32_u24 v136, v137, s0, v136
	v_lshlrev_b32_e32 v136, 2, v136
	s_mov_b64 s[44:45], s[56:57]
	global_load_dword v34, v136, s[44:45] nt
	s_add_u32 s44, s44, s40
	s_addc_u32 s45, s45, s41
	global_load_dword v35, v136, s[44:45] nt
	s_add_u32 s44, s44, s40
	s_addc_u32 s45, s45, s41
	global_load_dword v36, v136, s[44:45] nt
	s_add_u32 s44, s44, s40
	s_addc_u32 s45, s45, s41
	global_load_dword v37, v136, s[44:45] nt
	s_add_u32 s44, s44, s40
	s_addc_u32 s45, s45, s41
	global_load_dword v38, v136, s[44:45] nt
	s_add_u32 s44, s44, s40
	s_addc_u32 s45, s45, s41
	global_load_dword v39, v136, s[44:45] nt
	s_add_u32 s44, s44, s40
	s_addc_u32 s45, s45, s41
	global_load_dword v40, v136, s[44:45] nt
	s_add_u32 s44, s44, s40
	s_addc_u32 s45, s45, s41
	global_load_dword v41, v136, s[44:45] nt
	s_cmp_eq_u64 s[36:37], 0
	s_cbranch_scc1 .Lcv_ng_a_0
	s_lshl_b32 s61, s61, 2
	s_add_u32 s44, s58, s61
	s_addc_u32 s45, s59, 0
	global_load_dword v42, v141, s[44:45] offset:0
	global_load_dword v43, v141, s[44:45] offset:32
	global_load_dword v44, v141, s[44:45] offset:64
	global_load_dword v45, v141, s[44:45] offset:96
	global_load_dword v46, v141, s[44:45] offset:128
	global_load_dword v47, v141, s[44:45] offset:160
	global_load_dword v48, v141, s[44:45] offset:192
	global_load_dword v49, v141, s[44:45] offset:224

; #define LAS __attribute__((address_space(3)))
; __device__ __forceinline__ int fresh_tid() { int t; asm volatile("v_mov_b32 %0, %1" : "=v"(t) : "v"(threadIdx.x)); return t; }
; __device__ __forceinline__ int fresh_bid() { int t; asm volatile("s_mov_b32 %0, %1" : "=s"(t) : "s"(blockIdx.x)); return t; }
; #define ACC_ZERO(acc) _Pragma("unroll") for (int _a = 0; _a < 2; ++_a) _Pragma("unroll") for (int _b = 0; _b < 2; ++_b) _Pragma("unroll") for (int _m = 0; _m < 4; ++_m) \
;     _Pragma("unroll") for (int _n = 0; _n < 2; ++_n) acc[_a][_b][_m][_n] = (f32x4){0.f, 0.f, 0.f, 0.f}
; __device__ __forceinline__ void gemm_stage_first(const bf16_t* __restrict__ A, int lda, const bf16_t* __restrict__ Bt, int ldb, int brow, int bcol, LAS unsigned char* lds) {
;     const int tid = fresh_tid();
;     const int wvu = __builtin_amdgcn_readfirstlane(tid >> 6);
;     unsigned offA, offB;
;     { int _r, _c; stage_rc(tid * 16, _r, _c); offA = (unsigned)(_r * lda + _c) * 2u; offB = (unsigned)(_r * ldb + _c) * 2u; }
;     STAGE(SBo(0, 0), Bt, ldb, bcol, 0, offB); STAGE(SAo(0, 0), A, lda, brow, 0, offA);
;     STAGE(SBo(0, 1), Bt, ldb, bcol + HALF, 0, offB); STAGE(SAo(0, 1), A, lda, brow + HALF, 0, offA);
; }
; __device__ __forceinline__ void phase_gates(const Ctx& a, LAS unsigned char* lds) {
;     ...
;     for (int w = fresh_bid(); w < ntile; w += gridDim.x) {
;         int pm, pn; tile_of(w, nM, pm, pn);
;         Acc acc; ACC_ZERO(acc);
;         gemm_kloop<true>(acc, xb, DM, W, DM, pm * 256, pn * 256, DM / 64, lds);
;         { const int wn = w + (int)gridDim.x; if (wn < ntile) { int pm2, pn2; tile_of(wn, nM, pm2, pn2); gemm_stage_first(xb, DM, W, DM, pm2 * 256, pn2 * 256, lds); } }
.LBB0_751:
	s_or_b64 exec, exec, s[12:13]
	s_movk_i32 s1, 0x100
	s_waitcnt lgkmcnt(0)
	s_add_i32 s9, s1, s9
	s_cmpk_gt_i32 s9, 0x2ff
	s_cselect_b64 s[12:13], -1, 0
	s_and_b64 vcc, exec, s[12:13]
	s_cbranch_vccnz .LBB0_744
	s_ashr_i32 s1, s9, 31
	s_lshr_b32 s1, s1, 26
	s_add_i32 s1, s9, s1
	v_mov_b32 v1, v179
	s_and_b32 s8, s1, 0xffffc0
	v_ashrrev_i32_e32 v131, 31, v1
	s_lshl_b32 s1, s1, 2
	v_lshrrev_b32_e32 v131, 26, v131
	s_and_b32 s40, s1, 0xffffff00
	v_readfirstlane_b32 s1, v1
	v_lshlrev_b32_e32 v130, 4, v1
	v_add_u32_e32 v131, v1, v131
	v_bfe_i32 v1, v1, 27, 1
	v_lshrrev_b32_e32 v1, 22, v1
	v_add_u32_e32 v1, v130, v1
	v_and_b32_e32 v1, 0xfffffc00, v1
	v_sub_u32_e32 v1, v130, v1
	v_lshrrev_b32_e32 v130, 4, v1
	v_bitop3_b32 v130, v130, v1, 32 bitop3:0x6c
	v_ashrrev_i32_e32 v1, 31, v1
	v_lshrrev_b32_e32 v1, 26, v1
	v_add_u32_e32 v1, v130, v1
	s_sub_i32 s8, s9, s8
	s_ashr_i32 s1, s1, 6
	v_ashrrev_i32_e32 v1, 6, v1
	s_lshl_b32 s38, s8, 8
	v_ashrrev_i32_e32 v131, 6, v131
	v_mul_i32_i24_e32 v133, 64, v1
	s_mov_b32 s42, s27
	s_mov_b32 s8, s1
	v_lshlrev_b32_e32 v132, 3, v131
	v_lshlrev_b32_e32 v131, 5, v131
	v_sub_u32_e32 v130, v130, v133
	s_ashr_i32 s43, s42, 31
	v_and_b32_e32 v132, 0x1ffff0, v132
	v_and_b32_e32 v131, 32, v131
	v_ashrrev_i16_sdwa v130, v194, sext(v130) dst_sel:DWORD dst_unused:UNUSED_PAD src0_sel:DWORD src1_sel:BYTE_0
	s_lshl_b64 s[42:43], s[42:43], 7
	v_add_u32_sdwa v130, v131, sext(v130) dst_sel:DWORD dst_unused:UNUSED_PAD src0_sel:DWORD src1_sel:WORD_0
	v_add_lshl_u32 v1, v1, v132, 11
	s_add_u32 s42, s82, s42
	v_lshl_add_u32 v144, v130, 1, v1
	s_addc_u32 s43, s83, s43
	s_ashr_i32 s41, s40, 31
	v_lshl_add_u64 v[130:131], s[42:43], 0, v[144:145]
	s_lshl_b64 s[42:43], s[40:41], 11
	s_lshl_b32 s8, s8, 10
	v_lshl_add_u64 v[132:133], v[130:131], 0, s[42:43]
	s_or_b32 s42, s40, 64
	s_add_i32 s8, s8, 0
	s_ashr_i32 s43, s42, 31
	s_add_i32 m0, s8, 0x10000
	s_lshl_b64 s[42:43], s[42:43], 11
	global_load_lds_dwordx4 v[132:133], off
	v_lshl_add_u64 v[130:131], v[130:131], 0, s[42:43]
	s_add_i32 m0, s8, 0x12000
	s_mov_b32 s42, s27
	s_mov_b32 s8, s1
	global_load_lds_dwordx4 v[130:131], off
	s_ashr_i32 s43, s42, 31
	s_lshl_b64 s[42:43], s[42:43], 7
	s_add_u32 s42, s34, s42
	s_addc_u32 s43, s35, s43
	s_ashr_i32 s39, s38, 31
	v_lshl_add_u64 v[130:131], s[42:43], 0, v[144:145]
	s_lshl_b64 s[42:43], s[38:39], 11
	s_lshl_b32 s8, s8, 10
	v_lshl_add_u64 v[132:133], v[130:131], 0, s[42:43]
	s_or_b32 s42, s38, 64
	s_add_i32 s8, s8, 0
	s_ashr_i32 s43, s42, 31
	s_mov_b32 m0, s8
	s_lshl_b64 s[42:43], s[42:43], 11
	global_load_lds_dwordx4 v[132:133], off
	v_lshl_add_u64 v[130:131], v[130:131], 0, s[42:43]
	s_add_i32 m0, s8, 0x2000
	s_mov_b32 s42, s27
	s_mov_b32 s8, s1
	global_load_lds_dwordx4 v[130:131], off
	s_ashr_i32 s43, s42, 31
	s_or_b32 s44, s40, 0x80
	s_lshl_b64 s[42:43], s[42:43], 7
	s_add_u32 s42, s82, s42
	s_addc_u32 s43, s83, s43
	s_lshl_b32 s8, s8, 10
	s_ashr_i32 s45, s44, 31
	s_or_b32 s40, s40, 0xc0
	v_lshl_add_u64 v[130:131], s[42:43], 0, v[144:145]
	s_add_i32 s8, s8, 0
	s_lshl_b64 s[42:43], s[44:45], 11
	s_ashr_i32 s41, s40, 31
	s_add_i32 m0, s8, 0x14000
	v_lshl_add_u64 v[132:133], v[130:131], 0, s[42:43]
	s_lshl_b64 s[40:41], s[40:41], 11
	global_load_lds_dwordx4 v[132:133], off
	v_lshl_add_u64 v[130:131], v[130:131], 0, s[40:41]
	s_add_i32 m0, s8, 0x16000
	s_mov_b32 s40, s27
	global_load_lds_dwordx4 v[130:131], off
	s_ashr_i32 s41, s40, 31
	s_or_b32 s42, s38, 0x80
	s_lshl_b64 s[40:41], s[40:41], 7
	s_add_u32 s40, s34, s40
	s_addc_u32 s41, s35, s41
	s_lshl_b32 s1, s1, 10
	s_ashr_i32 s43, s42, 31
	s_or_b32 s38, s38, 0xc0
	v_lshl_add_u64 v[130:131], s[40:41], 0, v[144:145]
	s_add_i32 s1, s1, 0
	s_lshl_b64 s[40:41], s[42:43], 11
	s_ashr_i32 s39, s38, 31
	s_add_i32 m0, s1, 0x4000
	v_lshl_add_u64 v[132:133], v[130:131], 0, s[40:41]
	s_lshl_b64 s[38:39], s[38:39], 11
	global_load_lds_dwordx4 v[132:133], off
	v_lshl_add_u64 v[130:131], v[130:131], 0, s[38:39]
	s_add_i32 m0, s1, 0x6000
	s_nop 0
	global_load_lds_dwordx4 v[130:131], off
	s_branch .LBB0_744
